# GU K-loop: LDS-DMA saddr form (no VALU in load segments), s_setprio and redundant post-barrier lgkmcnt wait removed
# speedup vs baseline: 1.0068x; 1.0068x over previous
.LBB0_180:
	s_lshl_b32 s76, s69, 15
	s_add_u32 s12, s4, 0x31400000
	s_addc_u32 s13, s5, 0
	s_lshl_b64 s[18:19], s[76:77], 3
	s_add_u32 s4, s4, s18
	s_addc_u32 s5, s5, s19
	s_lshl_b32 s17, s14, 5
	s_add_i32 s41, s33, 0x18000
	s_and_b32 s17, s17, 0x60
	v_lshl_add_u64 v[14:15], v[14:15], 0, s[82:83]
	s_mov_b32 m0, s41
	s_add_i32 s42, s33, 0x1a000
	s_lshl_b32 s15, s16, 13
	s_lshl_b32 s20, s17, 7
	s_waitcnt vmcnt(2)
	s_barrier
	global_load_lds_dwordx4 v[14:15], off
	v_lshl_add_u64 v[12:13], v[12:13], 0, s[82:83]
	s_mov_b32 m0, s42
	s_add_i32 s43, s33, 0x8000
	s_add_i32 s44, s33, 0xa000
	global_load_lds_dwordx4 v[12:13], off
	v_lshl_add_u64 v[8:9], v[8:9], 0, s[82:83]
	s_mov_b32 m0, s43
	s_add_u32 s18, s6, 0x80080
	global_load_lds_dwordx4 v[8:9], off
	v_lshl_add_u64 v[8:9], v[10:11], 0, s[82:83]
	s_mov_b32 m0, s44
	s_addc_u32 s19, s7, 0
	s_add_i32 s45, s33, 0x1c000
	global_load_lds_dwordx4 v[8:9], off
	v_lshl_add_u64 v[8:9], s[18:19], 0, v[4:5]
	s_mov_b32 m0, s45
	s_add_i32 s46, s33, 0x1e000
	global_load_lds_dwordx4 v[8:9], off
	v_lshl_add_u64 v[8:9], s[18:19], 0, v[2:3]
	s_mov_b32 m0, s46
	v_lshlrev_b32_e32 v11, 2, v6
	global_load_lds_dwordx4 v[8:9], off
	v_bfe_u32 v9, v6, 4, 2
	v_and_b32_e32 v8, 15, v6
	v_lshlrev_b32_e32 v10, 4, v9
	v_lshl_or_b32 v10, v8, 6, v10
	v_and_b32_e32 v11, 32, v11
	v_bitop3_b32 v12, v10, s15, v11 bitop3:0xde
	v_bitop3_b32 v189, v10, s20, v11 bitop3:0xde
	v_add_u32_e32 v238, 0x10000, v189
	v_ashrrev_i32_e32 v11, 5, v6
	v_lshl_add_u64 v[6:7], v[6:7], 3, s[4:5]
	v_lshl_add_u64 v[170:171], v[6:7], 0, s[72:73]
	v_lshlrev_b32_e32 v6, 15, v21
	v_and_b32_e32 v6, 0xffff0000, v6
	v_lshl_add_u32 v6, v20, 12, v6
	v_and_b32_e32 v7, 1, v21
	v_lshl_or_b32 v6, v7, 6, v6
	v_lshl_add_u32 v172, v22, 1, v6
	v_lshlrev_b32_e32 v6, 15, v17
	s_cmp_lt_u32 s14, 4
	v_lshlrev_b32_e32 v10, 4, v16
	v_and_b32_e32 v6, 0xffff0000, v6
	v_lshl_or_b32 v188, s16, 6, v8
	s_waitcnt vmcnt(6)
	s_cselect_b64 s[14:15], -1, 0
	v_and_or_b32 v10, v10, 16, v8
	v_readlane_b32 s18, v255, 29
	v_lshlrev_b32_e32 v11, 2, v11
	s_lshl_b32 s16, s16, 9
	v_lshl_add_u32 v6, v18, 12, v6
	v_and_b32_e32 v7, 1, v17
	v_lshl_add_u32 v10, v10, 5, s18
	v_and_b32_e32 v11, -16, v11
	v_lshlrev_b32_e32 v13, 2, v9
	s_add_i32 s16, s18, s16
	v_lshlrev_b32_e32 v8, 5, v8
	v_lshl_or_b32 v6, v7, 6, v6
	v_readlane_b32 s4, v255, 34
	v_add3_u32 v190, v10, v11, v13
	s_ashr_i32 s47, s34, 31
	v_lshl_or_b32 v191, v9, 3, s17
	v_mov_b32_e32 v173, v5
	v_lshl_add_u32 v174, v19, 1, v6
	v_mov_b32_e32 v175, v5
	s_mov_b32 s48, 0
	v_mov_b64_e32 v[176:177], 0
	v_add_u32_e32 v192, s16, v8
	v_add_u32_e32 v193, 0, v12
	s_mov_b32 s24, s4
	v_readlane_b32 s49, v255, 12
	s_barrier
	v_readlane_b32 s5, v255, 35
	s_branch .LBB0_183

.LBB0_186:
	s_mov_b32 m0, s41
	s_add_u32 s54, s28, 0x80
	s_addc_u32 s55, s29, 0
	ds_read_b128 v[194:197], v193 offset:49152
	ds_read_b128 v[198:201], v193 offset:50176
	ds_read_b128 v[202:205], v193 offset:51200
	ds_read_b128 v[206:209], v193 offset:52224
	ds_read_b128 v[212:215], v193 offset:53248
	ds_read_b128 v[216:219], v193 offset:54272
	ds_read_b128 v[220:223], v193 offset:55296
	ds_read_b128 v[224:227], v193 offset:56320
	global_load_lds_dwordx4 v4, s[54:55]
	s_mov_b32 m0, s42
	s_add_u32 s6, s28, 0x80080
	s_addc_u32 s7, s29, 0
	global_load_lds_dwordx4 v2, s[54:55]
	s_mov_b32 m0, s45
	s_add_u32 s98, s30, 0xfff80080
	s_addc_u32 s99, s31, -1
	global_load_lds_dwordx4 v4, s[6:7]
	s_mov_b32 m0, s46
	s_nop 0
	global_load_lds_dwordx4 v2, s[6:7]
	s_mov_b32 m0, s43
	s_nop 0
	global_load_lds_dwordx4 v168, s[98:99]
	s_mov_b32 m0, s44
	s_nop 0
	global_load_lds_dwordx4 v166, s[98:99]
	s_waitcnt vmcnt(8)
	s_waitcnt lgkmcnt(0)
	s_barrier
	v_mfma_f32_16x16x32_bf16 v[10:13], v[158:161], v[194:197], v[10:13]
	v_mfma_f32_16x16x32_bf16 v[18:21], v[162:165], v[194:197], v[18:21]
	v_mfma_f32_16x16x32_bf16 v[26:29], v[158:161], v[202:205], v[26:29]
	v_mfma_f32_16x16x32_bf16 v[34:37], v[162:165], v[202:205], v[34:37]
	v_mfma_f32_16x16x32_bf16 v[180:183], v[158:161], v[212:215], v[42:45]
	v_mfma_f32_16x16x32_bf16 v[184:187], v[162:165], v[212:215], v[50:53]
	v_mfma_f32_16x16x32_bf16 v[158:161], v[158:161], v[220:223], v[58:61]
	v_mfma_f32_16x16x32_bf16 v[162:165], v[162:165], v[220:223], v[66:69]
	v_mfma_f32_16x16x32_bf16 v[66:69], v[150:153], v[198:201], v[10:13]
	v_mfma_f32_16x16x32_bf16 v[58:61], v[154:157], v[198:201], v[18:21]
	v_mfma_f32_16x16x32_bf16 v[50:53], v[150:153], v[206:209], v[26:29]
	v_mfma_f32_16x16x32_bf16 v[42:45], v[154:157], v[206:209], v[34:37]
	v_mfma_f32_16x16x32_bf16 v[34:37], v[150:153], v[216:219], v[180:183]
	v_mfma_f32_16x16x32_bf16 v[26:29], v[154:157], v[216:219], v[184:187]
	v_mfma_f32_16x16x32_bf16 v[18:21], v[150:153], v[224:227], v[158:161]
	v_mfma_f32_16x16x32_bf16 v[10:13], v[154:157], v[224:227], v[162:165]
	v_mfma_f32_16x16x32_bf16 v[6:9], v[142:145], v[194:197], v[6:9]
	v_mfma_f32_16x16x32_bf16 v[14:17], v[146:149], v[194:197], v[14:17]
	v_mfma_f32_16x16x32_bf16 v[22:25], v[142:145], v[202:205], v[22:25]
	v_mfma_f32_16x16x32_bf16 v[30:33], v[146:149], v[202:205], v[30:33]
	v_mfma_f32_16x16x32_bf16 v[150:153], v[142:145], v[212:215], v[38:41]
	v_mfma_f32_16x16x32_bf16 v[154:157], v[146:149], v[212:215], v[46:49]
	v_mfma_f32_16x16x32_bf16 v[142:145], v[142:145], v[220:223], v[54:57]
	v_mfma_f32_16x16x32_bf16 v[146:149], v[146:149], v[220:223], v[62:65]
	v_mfma_f32_16x16x32_bf16 v[62:65], v[74:77], v[198:201], v[6:9]
	v_mfma_f32_16x16x32_bf16 v[54:57], v[138:141], v[198:201], v[14:17]
	v_mfma_f32_16x16x32_bf16 v[46:49], v[74:77], v[206:209], v[22:25]
	v_mfma_f32_16x16x32_bf16 v[38:41], v[138:141], v[206:209], v[30:33]
	v_mfma_f32_16x16x32_bf16 v[30:33], v[74:77], v[216:219], v[150:153]
	v_mfma_f32_16x16x32_bf16 v[22:25], v[138:141], v[216:219], v[154:157]
	v_mfma_f32_16x16x32_bf16 v[14:17], v[74:77], v[224:227], v[142:145]
	v_mfma_f32_16x16x32_bf16 v[6:9], v[138:141], v[224:227], v[146:149]
	s_barrier
	s_add_i32 s53, s53, 2
	s_add_u32 s26, s26, 0x100
	s_addc_u32 s27, s27, 0
	s_add_u32 s25, s25, 0x100
	s_addc_u32 s52, s52, 0
	s_cmp_gt_u32 s53, 29
	s_cbranch_scc1 .LBB0_191
.LBB0_187:
	s_cmp_eq_u32 s53, 28
	s_cselect_b64 s[28:29], -1, 0
	s_and_b64 s[30:31], s[28:29], s[14:15]
	s_andn2_b64 s[6:7], exec, s[30:31]
	s_andn2_b64 vcc, exec, s[30:31]
	s_cbranch_vccnz .LBB0_189
	global_load_dwordx2 v[176:177], v[178:179], off
.LBB0_189:
	s_add_u32 s30, s26, 0xfff80080
	s_addc_u32 s31, s27, -1
	s_and_b64 s[28:29], s[28:29], exec
	s_cselect_b32 s31, s19, s31
	s_cselect_b32 s30, s50, s30
	s_cselect_b32 s29, s17, s52
	s_cselect_b32 s28, s51, s25
	s_add_i32 s54, 0, 0x10000
	s_add_i32 s56, 0, 0x14000
	ds_read_b128 v[74:77], v238
	ds_read_b128 v[138:141], v238 offset:1024
	ds_read_b128 v[142:145], v238 offset:2048
	ds_read_b128 v[146:149], v238 offset:3072
	ds_read_b128 v[150:153], v238 offset:16384
	ds_read_b128 v[154:157], v238 offset:17408
	ds_read_b128 v[158:161], v238 offset:18432
	ds_read_b128 v[162:165], v238 offset:19456
	s_add_i32 m0, s33, 0xc000
	ds_read_b128 v[180:183], v193
	ds_read_b128 v[184:187], v193 offset:1024
	ds_read_b128 v[194:197], v193 offset:2048
	ds_read_b128 v[198:201], v193 offset:3072
	ds_read_b128 v[202:205], v193 offset:4096
	ds_read_b128 v[212:215], v193 offset:5120
	ds_read_b128 v[216:219], v193 offset:6144
	ds_read_b128 v[220:223], v193 offset:7168
	global_load_lds_dwordx4 v172, s[26:27]
	s_add_i32 m0, s33, 0xe000
	s_nop 0
	global_load_lds_dwordx4 v174, s[26:27]
	s_waitcnt vmcnt(8)
	s_waitcnt lgkmcnt(0)
	s_barrier
	v_mfma_f32_16x16x32_bf16 v[134:137], v[74:77], v[180:183], v[134:137]
	v_mfma_f32_16x16x32_bf16 v[126:129], v[142:145], v[180:183], v[126:129]
	v_mfma_f32_16x16x32_bf16 v[118:121], v[74:77], v[194:197], v[118:121]
	v_mfma_f32_16x16x32_bf16 v[110:113], v[142:145], v[194:197], v[110:113]
	v_mfma_f32_16x16x32_bf16 v[102:105], v[74:77], v[202:205], v[102:105]
	v_mfma_f32_16x16x32_bf16 v[94:97], v[142:145], v[202:205], v[94:97]
	v_mfma_f32_16x16x32_bf16 v[86:89], v[74:77], v[216:219], v[86:89]
	v_mfma_f32_16x16x32_bf16 v[78:81], v[142:145], v[216:219], v[78:81]
	v_mfma_f32_16x16x32_bf16 v[134:137], v[138:141], v[184:187], v[134:137]
	v_mfma_f32_16x16x32_bf16 v[126:129], v[146:149], v[184:187], v[126:129]
	v_mfma_f32_16x16x32_bf16 v[118:121], v[138:141], v[198:201], v[118:121]
	v_mfma_f32_16x16x32_bf16 v[110:113], v[146:149], v[198:201], v[110:113]
	v_mfma_f32_16x16x32_bf16 v[102:105], v[138:141], v[212:215], v[102:105]
	v_mfma_f32_16x16x32_bf16 v[94:97], v[146:149], v[212:215], v[94:97]
	v_mfma_f32_16x16x32_bf16 v[86:89], v[138:141], v[220:223], v[86:89]
	v_mfma_f32_16x16x32_bf16 v[78:81], v[146:149], v[220:223], v[78:81]
	v_mfma_f32_16x16x32_bf16 v[130:133], v[150:153], v[180:183], v[130:133]
	v_mfma_f32_16x16x32_bf16 v[122:125], v[158:161], v[180:183], v[122:125]
	v_mfma_f32_16x16x32_bf16 v[114:117], v[150:153], v[194:197], v[114:117]
	v_mfma_f32_16x16x32_bf16 v[106:109], v[158:161], v[194:197], v[106:109]
	v_mfma_f32_16x16x32_bf16 v[98:101], v[150:153], v[202:205], v[98:101]
	v_mfma_f32_16x16x32_bf16 v[90:93], v[158:161], v[202:205], v[90:93]
	v_mfma_f32_16x16x32_bf16 v[82:85], v[150:153], v[216:219], v[82:85]
	v_mfma_f32_16x16x32_bf16 v[70:73], v[158:161], v[216:219], v[70:73]
	v_mfma_f32_16x16x32_bf16 v[130:133], v[154:157], v[184:187], v[130:133]
	v_mfma_f32_16x16x32_bf16 v[122:125], v[162:165], v[184:187], v[122:125]
	v_mfma_f32_16x16x32_bf16 v[114:117], v[154:157], v[198:201], v[114:117]
	v_mfma_f32_16x16x32_bf16 v[106:109], v[162:165], v[198:201], v[106:109]
	v_mfma_f32_16x16x32_bf16 v[98:101], v[154:157], v[212:215], v[98:101]
	v_mfma_f32_16x16x32_bf16 v[90:93], v[162:165], v[212:215], v[90:93]
	v_mfma_f32_16x16x32_bf16 v[82:85], v[154:157], v[220:223], v[82:85]
	v_mfma_f32_16x16x32_bf16 v[70:73], v[162:165], v[220:223], v[70:73]
	s_barrier
	s_add_i32 s54, s54, s35
	s_mov_b32 m0, s54
	ds_read_b128 v[194:197], v193 offset:16384
	ds_read_b128 v[198:201], v193 offset:17408
	ds_read_b128 v[202:205], v193 offset:18432
	ds_read_b128 v[212:215], v193 offset:19456
	ds_read_b128 v[216:219], v193 offset:20480
	ds_read_b128 v[220:223], v193 offset:21504
	ds_read_b128 v[224:227], v193 offset:22528
	ds_read_b128 v[228:231], v193 offset:23552
	global_load_lds_dwordx4 v4, s[28:29]
	s_add_i32 m0, s54, 0x2000
	s_add_u32 s54, s28, 0x80000
	s_addc_u32 s55, s29, 0
	global_load_lds_dwordx4 v2, s[28:29]
	s_add_i32 s56, s56, s35
	s_mov_b32 m0, s56
	s_nop 0
	global_load_lds_dwordx4 v4, s[54:55]
	s_add_i32 m0, s56, 0x2000
	s_nop 0
	global_load_lds_dwordx4 v2, s[54:55]
	s_mov_b32 m0, s33
	s_nop 0
	global_load_lds_dwordx4 v168, s[30:31]
	s_mov_b32 m0, s38
	s_nop 0
	global_load_lds_dwordx4 v166, s[30:31]
	s_waitcnt vmcnt(8)
	s_waitcnt lgkmcnt(0)
	s_barrier
	v_mfma_f32_16x16x32_bf16 v[66:69], v[74:77], v[194:197], v[66:69]
	v_mfma_f32_16x16x32_bf16 v[58:61], v[142:145], v[194:197], v[58:61]
	v_mfma_f32_16x16x32_bf16 v[50:53], v[74:77], v[202:205], v[50:53]
	v_mfma_f32_16x16x32_bf16 v[42:45], v[142:145], v[202:205], v[42:45]
	v_mfma_f32_16x16x32_bf16 v[248:251], v[74:77], v[216:219], v[34:37]
	v_mfma_f32_16x16x32_bf16 v[206:209], v[142:145], v[216:219], v[26:29]
	v_mfma_f32_16x16x32_bf16 v[74:77], v[74:77], v[224:227], v[18:21]
	v_mfma_f32_16x16x32_bf16 v[142:145], v[142:145], v[224:227], v[10:13]
	v_mfma_f32_16x16x32_bf16 v[10:13], v[138:141], v[198:201], v[66:69]
	v_mfma_f32_16x16x32_bf16 v[18:21], v[146:149], v[198:201], v[58:61]
	v_mfma_f32_16x16x32_bf16 v[26:29], v[138:141], v[212:215], v[50:53]
	v_mfma_f32_16x16x32_bf16 v[34:37], v[146:149], v[212:215], v[42:45]
	v_mfma_f32_16x16x32_bf16 v[42:45], v[138:141], v[220:223], v[248:251]
	v_mfma_f32_16x16x32_bf16 v[50:53], v[146:149], v[220:223], v[206:209]
	v_mfma_f32_16x16x32_bf16 v[58:61], v[138:141], v[228:231], v[74:77]
	v_mfma_f32_16x16x32_bf16 v[66:69], v[146:149], v[228:231], v[142:145]
	v_mfma_f32_16x16x32_bf16 v[62:65], v[150:153], v[194:197], v[62:65]
	v_mfma_f32_16x16x32_bf16 v[54:57], v[158:161], v[194:197], v[54:57]
	v_mfma_f32_16x16x32_bf16 v[46:49], v[150:153], v[202:205], v[46:49]
	v_mfma_f32_16x16x32_bf16 v[38:41], v[158:161], v[202:205], v[38:41]
	v_mfma_f32_16x16x32_bf16 v[74:77], v[150:153], v[216:219], v[30:33]
	v_mfma_f32_16x16x32_bf16 v[138:141], v[158:161], v[216:219], v[22:25]
	v_mfma_f32_16x16x32_bf16 v[142:145], v[150:153], v[224:227], v[14:17]
	v_mfma_f32_16x16x32_bf16 v[146:149], v[158:161], v[224:227], v[6:9]
	v_mfma_f32_16x16x32_bf16 v[6:9], v[154:157], v[198:201], v[62:65]
	v_mfma_f32_16x16x32_bf16 v[14:17], v[162:165], v[198:201], v[54:57]
	v_mfma_f32_16x16x32_bf16 v[22:25], v[154:157], v[212:215], v[46:49]
	v_mfma_f32_16x16x32_bf16 v[30:33], v[162:165], v[212:215], v[38:41]
	v_mfma_f32_16x16x32_bf16 v[38:41], v[154:157], v[220:223], v[74:77]
	v_mfma_f32_16x16x32_bf16 v[46:49], v[162:165], v[220:223], v[138:141]
	v_mfma_f32_16x16x32_bf16 v[54:57], v[154:157], v[228:231], v[142:145]
	v_mfma_f32_16x16x32_bf16 v[62:65], v[162:165], v[228:231], v[146:149]
	s_barrier
	ds_read_b128 v[158:161], v238 offset:32768
	ds_read_b128 v[150:153], v238 offset:33792
	ds_read_b128 v[162:165], v238 offset:34816
	ds_read_b128 v[154:157], v238 offset:35840
	ds_read_b128 v[142:145], v238 offset:49152
	ds_read_b128 v[74:77], v238 offset:50176
	ds_read_b128 v[146:149], v238 offset:51200
	ds_read_b128 v[138:141], v238 offset:52224
	s_add_u32 s30, s30, 0x80000
	s_addc_u32 s31, s31, 0
	s_mov_b32 m0, s39
	ds_read_b128 v[194:197], v193 offset:32768
	ds_read_b128 v[198:201], v193 offset:33792
	ds_read_b128 v[202:205], v193 offset:34816
	ds_read_b128 v[206:209], v193 offset:35840
	ds_read_b128 v[212:215], v193 offset:36864
	ds_read_b128 v[216:219], v193 offset:37888
	ds_read_b128 v[220:223], v193 offset:38912
	ds_read_b128 v[224:227], v193 offset:39936
	global_load_lds_dwordx4 v168, s[30:31]
	s_mov_b32 m0, s40
	s_nop 0
	global_load_lds_dwordx4 v166, s[30:31]
	s_waitcnt vmcnt(8)
	s_waitcnt lgkmcnt(0)
	s_barrier
	v_mfma_f32_16x16x32_bf16 v[134:137], v[158:161], v[194:197], v[134:137]
	v_mfma_f32_16x16x32_bf16 v[126:129], v[162:165], v[194:197], v[126:129]
	v_mfma_f32_16x16x32_bf16 v[118:121], v[158:161], v[202:205], v[118:121]
	v_mfma_f32_16x16x32_bf16 v[110:113], v[162:165], v[202:205], v[110:113]
	v_mfma_f32_16x16x32_bf16 v[102:105], v[158:161], v[212:215], v[102:105]
	v_mfma_f32_16x16x32_bf16 v[94:97], v[162:165], v[212:215], v[94:97]
	v_mfma_f32_16x16x32_bf16 v[86:89], v[158:161], v[220:223], v[86:89]
	v_mfma_f32_16x16x32_bf16 v[78:81], v[162:165], v[220:223], v[78:81]
	v_mfma_f32_16x16x32_bf16 v[134:137], v[150:153], v[198:201], v[134:137]
	v_mfma_f32_16x16x32_bf16 v[126:129], v[154:157], v[198:201], v[126:129]
	v_mfma_f32_16x16x32_bf16 v[118:121], v[150:153], v[206:209], v[118:121]
	v_mfma_f32_16x16x32_bf16 v[110:113], v[154:157], v[206:209], v[110:113]
	v_mfma_f32_16x16x32_bf16 v[102:105], v[150:153], v[216:219], v[102:105]
	v_mfma_f32_16x16x32_bf16 v[94:97], v[154:157], v[216:219], v[94:97]
	v_mfma_f32_16x16x32_bf16 v[86:89], v[150:153], v[224:227], v[86:89]
	v_mfma_f32_16x16x32_bf16 v[78:81], v[154:157], v[224:227], v[78:81]
	v_mfma_f32_16x16x32_bf16 v[130:133], v[142:145], v[194:197], v[130:133]
	v_mfma_f32_16x16x32_bf16 v[122:125], v[146:149], v[194:197], v[122:125]
	v_mfma_f32_16x16x32_bf16 v[114:117], v[142:145], v[202:205], v[114:117]
	v_mfma_f32_16x16x32_bf16 v[106:109], v[146:149], v[202:205], v[106:109]
	v_mfma_f32_16x16x32_bf16 v[98:101], v[142:145], v[212:215], v[98:101]
	v_mfma_f32_16x16x32_bf16 v[90:93], v[146:149], v[212:215], v[90:93]
	v_mfma_f32_16x16x32_bf16 v[82:85], v[142:145], v[220:223], v[82:85]
	v_mfma_f32_16x16x32_bf16 v[70:73], v[146:149], v[220:223], v[70:73]
	v_mfma_f32_16x16x32_bf16 v[130:133], v[74:77], v[198:201], v[130:133]
	v_mfma_f32_16x16x32_bf16 v[122:125], v[138:141], v[198:201], v[122:125]
	v_mfma_f32_16x16x32_bf16 v[114:117], v[74:77], v[206:209], v[114:117]
	v_mfma_f32_16x16x32_bf16 v[106:109], v[138:141], v[206:209], v[106:109]
	v_mfma_f32_16x16x32_bf16 v[98:101], v[74:77], v[216:219], v[98:101]
	v_mfma_f32_16x16x32_bf16 v[90:93], v[138:141], v[216:219], v[90:93]
	v_mfma_f32_16x16x32_bf16 v[82:85], v[74:77], v[224:227], v[82:85]
	v_mfma_f32_16x16x32_bf16 v[70:73], v[138:141], v[224:227], v[70:73]
	s_barrier
	s_and_b64 vcc, exec, s[6:7]
	s_cbranch_vccnz .LBB0_186
	v_ffbh_u32_e32 v194, v177
	v_min_u32_e32 v196, 32, v194
	v_lshlrev_b64 v[194:195], v196, v[176:177]
	v_min_u32_e32 v194, 1, v194
	v_or_b32_e32 v194, v195, v194
	v_cvt_f32_u32_e32 v194, v194
	v_sub_u32_e32 v195, 32, v196
	v_ldexp_f32 v194, v194, v195
	v_mul_f32_e32 v194, 0x33800000, v194
	v_fmamk_f32 v194, v194, 0x3a000000, v232
	v_rsq_f32_e32 v194, v194
	ds_write_b32 v190, v194
	s_branch .LBB0_186
